# GEMM epilogue row stores marked nt (streaming) so the written tiles do not displace the re-read operand tiles in the XCD's L2
# speedup vs baseline: 1.0097x; 1.0097x over previous
; DI u16 f2bf(float x) { return (u16)(pack2(x, 0.f) & 0xffffu); }
; DI int crow(int i, int h) { return (i & 3) + 8 * (i >> 2) + 4 * h; }
; DI void phase_inproj(const Params& p, int l, char* smem, int tid) {
;     ...
; #pragma unroll
;     for (int mb = 0; mb < 2; mb++)
; #pragma unroll
;       for (int nb = 0; nb < 2; nb++) {
;         const int rowb = m0 + wm * 64 + mb * 32, colb = n0 + wn * 64 + nb * 32, col = colb + r;
;         if (colb < 1792) {
;           const float qs = (colb < 256) ? 0.125f * LOG2E : 1.f;
; #pragma unroll
;           for (int i = 0; i < 16; i++) p.Pk[(size_t)(rowb + crow(i, h)) * PKW + col] = f2bf(acc[mb][nb][i] * qs);
;         } else if (colb < 2592) {
; #pragma unroll
;           for (int i = 0; i < 16; i++) p.Pt[(size_t)(rowb + crow(i, h)) * PTW + col - 1792] = f2bf(acc[mb][nb][i]);
;         }
;       }
.Lip_rows_pk_ns:
	s_mul_i32 s2, s0, 0x70000
	s_lshl_b32 s3, s1, 8
	s_add_u32 s2, s2, s3
	s_add_u32 s2, s2, 0x4400000
	s_add_u32 s6, s96, s2
	s_addc_u32 s7, s97, 0
	v_cvt_pk_bf16_f32 v66, v2, v3
	v_cvt_pk_bf16_f32 v67, v4, v5
	ds_write_b64 v118, v[66:67] offset:0
	v_cvt_pk_bf16_f32 v68, v6, v7
	v_cvt_pk_bf16_f32 v69, v8, v9
	ds_write_b64 v118, v[68:69] offset:16
	v_cvt_pk_bf16_f32 v70, v10, v11
	v_cvt_pk_bf16_f32 v71, v12, v13
	ds_write_b64 v118, v[70:71] offset:32
	v_cvt_pk_bf16_f32 v72, v14, v15
	v_cvt_pk_bf16_f32 v73, v16, v17
	ds_write_b64 v118, v[72:73] offset:48
	v_cvt_pk_bf16_f32 v66, v18, v19
	v_cvt_pk_bf16_f32 v67, v20, v21
	ds_write_b64 v118, v[66:67] offset:64
	v_cvt_pk_bf16_f32 v68, v22, v23
	v_cvt_pk_bf16_f32 v69, v24, v25
	ds_write_b64 v118, v[68:69] offset:80
	v_cvt_pk_bf16_f32 v70, v26, v27
	v_cvt_pk_bf16_f32 v71, v28, v29
	ds_write_b64 v118, v[70:71] offset:96
	v_cvt_pk_bf16_f32 v72, v30, v31
	v_cvt_pk_bf16_f32 v73, v32, v33
	ds_write_b64 v118, v[72:73] offset:112
	v_cvt_pk_bf16_f32 v66, v34, v35
	v_cvt_pk_bf16_f32 v67, v36, v37
	ds_write_b64 v118, v[66:67] offset:4608
	v_cvt_pk_bf16_f32 v68, v38, v39
	v_cvt_pk_bf16_f32 v69, v40, v41
	ds_write_b64 v118, v[68:69] offset:4624
	v_cvt_pk_bf16_f32 v70, v42, v43
	v_cvt_pk_bf16_f32 v71, v44, v45
	ds_write_b64 v118, v[70:71] offset:4640
	v_cvt_pk_bf16_f32 v72, v46, v47
	v_cvt_pk_bf16_f32 v73, v48, v49
	ds_write_b64 v118, v[72:73] offset:4656
	v_cvt_pk_bf16_f32 v66, v50, v51
	v_cvt_pk_bf16_f32 v67, v52, v53
	ds_write_b64 v118, v[66:67] offset:4672
	v_cvt_pk_bf16_f32 v68, v54, v55
	v_cvt_pk_bf16_f32 v69, v56, v57
	ds_write_b64 v118, v[68:69] offset:4688
	v_cvt_pk_bf16_f32 v70, v58, v59
	v_cvt_pk_bf16_f32 v71, v60, v61
	ds_write_b64 v118, v[70:71] offset:4704
	v_cvt_pk_bf16_f32 v72, v62, v63
	v_cvt_pk_bf16_f32 v73, v64, v65
	ds_write_b64 v118, v[72:73] offset:4720
	ds_read_b128 v[74:77], v119 offset:0
	ds_read_b128 v[78:81], v119 offset:1152
	ds_read_b128 v[82:85], v119 offset:2304
	ds_read_b128 v[86:89], v119 offset:3456
	ds_read_b128 v[90:93], v119 offset:4608
	ds_read_b128 v[94:97], v119 offset:5760
	ds_read_b128 v[122:125], v119 offset:6912
	ds_read_b128 v[126:129], v119 offset:8064
	s_waitcnt lgkmcnt(7)
	global_store_dwordx4 v120, v[74:77], s[6:7] nt
	s_add_u32 s6, s6, 0x7000
	s_addc_u32 s7, s7, 0
	s_waitcnt lgkmcnt(6)
	global_store_dwordx4 v120, v[78:81], s[6:7] nt
	s_add_u32 s6, s6, 0x7000
	s_addc_u32 s7, s7, 0
	s_waitcnt lgkmcnt(5)
	global_store_dwordx4 v120, v[82:85], s[6:7] nt
	s_add_u32 s6, s6, 0x7000
	s_addc_u32 s7, s7, 0
	s_waitcnt lgkmcnt(4)
	global_store_dwordx4 v120, v[86:89], s[6:7] nt
	s_add_u32 s6, s6, 0x7000
	s_addc_u32 s7, s7, 0
	s_waitcnt lgkmcnt(3)
	global_store_dwordx4 v120, v[90:93], s[6:7] nt
	s_add_u32 s6, s6, 0x7000
	s_addc_u32 s7, s7, 0
	s_waitcnt lgkmcnt(2)
	global_store_dwordx4 v120, v[94:97], s[6:7] nt
	s_add_u32 s6, s6, 0x7000
	s_addc_u32 s7, s7, 0
	s_waitcnt lgkmcnt(1)
	global_store_dwordx4 v120, v[122:125], s[6:7] nt
	s_add_u32 s6, s6, 0x7000
	s_addc_u32 s7, s7, 0
	s_waitcnt lgkmcnt(0)
	global_store_dwordx4 v120, v[126:129], s[6:7] nt
	s_branch .Lip_epi_done
.Lip_rows_pt:
	s_mul_i32 s2, s0, 0x32000
	s_lshl_b32 s3, s1, 8
	s_sub_u32 s3, s3, 0xe00
	s_add_u32 s2, s2, s3
	s_add_u32 s2, s2, 0xbb00000
	s_add_u32 s6, s96, s2
	s_addc_u32 s7, s97, 0
	v_cvt_pk_bf16_f32 v66, v2, v3
	v_cvt_pk_bf16_f32 v67, v4, v5
	ds_write_b64 v118, v[66:67] offset:0
	v_cvt_pk_bf16_f32 v68, v6, v7
	v_cvt_pk_bf16_f32 v69, v8, v9
	ds_write_b64 v118, v[68:69] offset:16
	v_cvt_pk_bf16_f32 v70, v10, v11
	v_cvt_pk_bf16_f32 v71, v12, v13
	ds_write_b64 v118, v[70:71] offset:32
	v_cvt_pk_bf16_f32 v72, v14, v15
	v_cvt_pk_bf16_f32 v73, v16, v17
	ds_write_b64 v118, v[72:73] offset:48
	v_cvt_pk_bf16_f32 v66, v18, v19
	v_cvt_pk_bf16_f32 v67, v20, v21
	ds_write_b64 v118, v[66:67] offset:64
	v_cvt_pk_bf16_f32 v68, v22, v23
	v_cvt_pk_bf16_f32 v69, v24, v25
	ds_write_b64 v118, v[68:69] offset:80
	v_cvt_pk_bf16_f32 v70, v26, v27
	v_cvt_pk_bf16_f32 v71, v28, v29
	ds_write_b64 v118, v[70:71] offset:96
	v_cvt_pk_bf16_f32 v72, v30, v31
	v_cvt_pk_bf16_f32 v73, v32, v33
	ds_write_b64 v118, v[72:73] offset:112
	v_cvt_pk_bf16_f32 v66, v34, v35
	v_cvt_pk_bf16_f32 v67, v36, v37
	ds_write_b64 v118, v[66:67] offset:4608
	v_cvt_pk_bf16_f32 v68, v38, v39
	v_cvt_pk_bf16_f32 v69, v40, v41
	ds_write_b64 v118, v[68:69] offset:4624
	v_cvt_pk_bf16_f32 v70, v42, v43
	v_cvt_pk_bf16_f32 v71, v44, v45
	ds_write_b64 v118, v[70:71] offset:4640
	v_cvt_pk_bf16_f32 v72, v46, v47
	v_cvt_pk_bf16_f32 v73, v48, v49
	ds_write_b64 v118, v[72:73] offset:4656
	v_cvt_pk_bf16_f32 v66, v50, v51
	v_cvt_pk_bf16_f32 v67, v52, v53
	ds_write_b64 v118, v[66:67] offset:4672
	v_cvt_pk_bf16_f32 v68, v54, v55
	v_cvt_pk_bf16_f32 v69, v56, v57
	ds_write_b64 v118, v[68:69] offset:4688
	v_cvt_pk_bf16_f32 v70, v58, v59
	v_cvt_pk_bf16_f32 v71, v60, v61
	ds_write_b64 v118, v[70:71] offset:4704
	v_cvt_pk_bf16_f32 v72, v62, v63
	v_cvt_pk_bf16_f32 v73, v64, v65
	ds_write_b64 v118, v[72:73] offset:4720
	ds_read_b128 v[74:77], v119 offset:0
	ds_read_b128 v[78:81], v119 offset:1152
	ds_read_b128 v[82:85], v119 offset:2304
	ds_read_b128 v[86:89], v119 offset:3456
	ds_read_b128 v[90:93], v119 offset:4608
	ds_read_b128 v[94:97], v119 offset:5760
	ds_read_b128 v[122:125], v119 offset:6912
	ds_read_b128 v[126:129], v119 offset:8064
	s_waitcnt lgkmcnt(7)
	global_store_dwordx4 v121, v[74:77], s[6:7] nt
	s_add_u32 s6, s6, 0x3200
	s_addc_u32 s7, s7, 0
	s_waitcnt lgkmcnt(6)
	global_store_dwordx4 v121, v[78:81], s[6:7] nt
	s_add_u32 s6, s6, 0x3200
	s_addc_u32 s7, s7, 0
	s_waitcnt lgkmcnt(5)
	global_store_dwordx4 v121, v[82:85], s[6:7] nt
	s_add_u32 s6, s6, 0x3200
	s_addc_u32 s7, s7, 0
	s_waitcnt lgkmcnt(4)
	global_store_dwordx4 v121, v[86:89], s[6:7] nt
	s_add_u32 s6, s6, 0x3200
	s_addc_u32 s7, s7, 0
	s_waitcnt lgkmcnt(3)
	global_store_dwordx4 v121, v[90:93], s[6:7] nt
	s_add_u32 s6, s6, 0x3200
	s_addc_u32 s7, s7, 0
	s_waitcnt lgkmcnt(2)
	global_store_dwordx4 v121, v[94:97], s[6:7] nt
	s_add_u32 s6, s6, 0x3200
	s_addc_u32 s7, s7, 0
	s_waitcnt lgkmcnt(1)
	global_store_dwordx4 v121, v[122:125], s[6:7] nt
	s_add_u32 s6, s6, 0x3200
	s_addc_u32 s7, s7, 0
	s_waitcnt lgkmcnt(0)
	global_store_dwordx4 v121, v[126:129], s[6:7] nt
	s_branch .Lip_epi_done

; DI float bflo(unsigned v) { return __uint_as_float(v << 16); }
; DI float bfhi(unsigned v) { return __uint_as_float(v & 0xffff0000u); }
; DI void phase_merge(const Params& p, int l, char* smem, int tid) {
;     ...
; #pragma unroll
;       for (int b2 = 0; b2 < 2; b2++)
; #pragma unroll
;         for (int e = 0; e < 8; e++) { accT[0][b2][2 * e] += bflo(sg[b2][e]) * t[0][b2][2 * e]; accT[0][b2][2 * e + 1] += bfhi(sg[b2][e]) * t[0][b2][2 * e + 1]; }
.Lmgt_kdone:
	s_nop 7
	s_nop 7
	v_lshlrev_b32_e32 v147, 16, v156
	v_and_b32_e32 v149, 0xffff0000, v156
	v_fmac_f32_e32 v2, v147, v66
	v_fmac_f32_e32 v3, v149, v67
	v_lshlrev_b32_e32 v151, 16, v157
	v_and_b32_e32 v153, 0xffff0000, v157
	v_fmac_f32_e32 v4, v151, v68
	v_fmac_f32_e32 v5, v153, v69
	v_lshlrev_b32_e32 v147, 16, v158
	v_and_b32_e32 v149, 0xffff0000, v158
	v_fmac_f32_e32 v6, v147, v70
	v_fmac_f32_e32 v7, v149, v71
	v_lshlrev_b32_e32 v151, 16, v159
	v_and_b32_e32 v153, 0xffff0000, v159
	v_fmac_f32_e32 v8, v151, v72
	v_fmac_f32_e32 v9, v153, v73
	v_lshlrev_b32_e32 v147, 16, v160
	v_and_b32_e32 v149, 0xffff0000, v160
	v_fmac_f32_e32 v10, v147, v74
	v_fmac_f32_e32 v11, v149, v75
	v_lshlrev_b32_e32 v151, 16, v161
	v_and_b32_e32 v153, 0xffff0000, v161
	v_fmac_f32_e32 v12, v151, v76
	v_fmac_f32_e32 v13, v153, v77
	v_lshlrev_b32_e32 v147, 16, v162
	v_and_b32_e32 v149, 0xffff0000, v162
	v_fmac_f32_e32 v14, v147, v78
	v_fmac_f32_e32 v15, v149, v79
	v_lshlrev_b32_e32 v151, 16, v163
	v_and_b32_e32 v153, 0xffff0000, v163
	v_fmac_f32_e32 v16, v151, v80
	v_fmac_f32_e32 v17, v153, v81
	v_lshlrev_b32_e32 v147, 16, v164
	v_and_b32_e32 v149, 0xffff0000, v164
	v_fmac_f32_e32 v18, v147, v82
	v_fmac_f32_e32 v19, v149, v83
	v_lshlrev_b32_e32 v151, 16, v165
	v_and_b32_e32 v153, 0xffff0000, v165
	v_fmac_f32_e32 v20, v151, v84
	v_fmac_f32_e32 v21, v153, v85
	v_lshlrev_b32_e32 v147, 16, v166
	v_and_b32_e32 v149, 0xffff0000, v166
	v_fmac_f32_e32 v22, v147, v86
	v_fmac_f32_e32 v23, v149, v87
	v_lshlrev_b32_e32 v151, 16, v167
	v_and_b32_e32 v153, 0xffff0000, v167
	v_fmac_f32_e32 v24, v151, v88
	v_fmac_f32_e32 v25, v153, v89
	v_lshlrev_b32_e32 v147, 16, v168
	v_and_b32_e32 v149, 0xffff0000, v168
	v_fmac_f32_e32 v26, v147, v90
	v_fmac_f32_e32 v27, v149, v91
	v_lshlrev_b32_e32 v151, 16, v169
	v_and_b32_e32 v153, 0xffff0000, v169
	v_fmac_f32_e32 v28, v151, v92
	v_fmac_f32_e32 v29, v153, v93
	v_lshlrev_b32_e32 v147, 16, v170
	v_and_b32_e32 v149, 0xffff0000, v170
	v_fmac_f32_e32 v30, v147, v94
	v_fmac_f32_e32 v31, v149, v95
	v_lshlrev_b32_e32 v151, 16, v171
	v_and_b32_e32 v153, 0xffff0000, v171
	v_fmac_f32_e32 v32, v151, v96
	v_fmac_f32_e32 v33, v153, v97
	v_lshlrev_b32_e32 v147, 16, v172
	v_and_b32_e32 v149, 0xffff0000, v172
	v_fmac_f32_e32 v34, v147, v98
	v_fmac_f32_e32 v35, v149, v99
	v_lshlrev_b32_e32 v151, 16, v173
	v_and_b32_e32 v153, 0xffff0000, v173
	v_fmac_f32_e32 v36, v151, v100
	v_fmac_f32_e32 v37, v153, v101
	v_lshlrev_b32_e32 v147, 16, v174
	v_and_b32_e32 v149, 0xffff0000, v174
	v_fmac_f32_e32 v38, v147, v102
	v_fmac_f32_e32 v39, v149, v103
	v_lshlrev_b32_e32 v151, 16, v175
	v_and_b32_e32 v153, 0xffff0000, v175
	v_fmac_f32_e32 v40, v151, v104
	v_fmac_f32_e32 v41, v153, v105
	v_lshlrev_b32_e32 v147, 16, v176
	v_and_b32_e32 v149, 0xffff0000, v176
	v_fmac_f32_e32 v42, v147, v106
	v_fmac_f32_e32 v43, v149, v107
	v_lshlrev_b32_e32 v151, 16, v177
	v_and_b32_e32 v153, 0xffff0000, v177
	v_fmac_f32_e32 v44, v151, v108
	v_fmac_f32_e32 v45, v153, v109
	v_lshlrev_b32_e32 v147, 16, v178
	v_and_b32_e32 v149, 0xffff0000, v178
	v_fmac_f32_e32 v46, v147, v110
	v_fmac_f32_e32 v47, v149, v111
	v_lshlrev_b32_e32 v151, 16, v179
	v_and_b32_e32 v153, 0xffff0000, v179
	v_fmac_f32_e32 v48, v151, v112
	v_fmac_f32_e32 v49, v153, v113
	v_lshlrev_b32_e32 v147, 16, v180
	v_and_b32_e32 v149, 0xffff0000, v180
	v_fmac_f32_e32 v50, v147, v114
	v_fmac_f32_e32 v51, v149, v115
	v_lshlrev_b32_e32 v151, 16, v181
	v_and_b32_e32 v153, 0xffff0000, v181
	v_fmac_f32_e32 v52, v151, v116
	v_fmac_f32_e32 v53, v153, v117
	v_lshlrev_b32_e32 v147, 16, v182
	v_and_b32_e32 v149, 0xffff0000, v182
	v_fmac_f32_e32 v54, v147, v118
	v_fmac_f32_e32 v55, v149, v119
	v_lshlrev_b32_e32 v151, 16, v183
	v_and_b32_e32 v153, 0xffff0000, v183
	v_fmac_f32_e32 v56, v151, v120
	v_fmac_f32_e32 v57, v153, v121
	v_lshlrev_b32_e32 v147, 16, v184
	v_and_b32_e32 v149, 0xffff0000, v184
	v_fmac_f32_e32 v58, v147, v122
	v_fmac_f32_e32 v59, v149, v123
	v_lshlrev_b32_e32 v151, 16, v185
	v_and_b32_e32 v153, 0xffff0000, v185
	v_fmac_f32_e32 v60, v151, v124
	v_fmac_f32_e32 v61, v153, v125
	v_lshlrev_b32_e32 v147, 16, v186
	v_and_b32_e32 v149, 0xffff0000, v186
	v_fmac_f32_e32 v62, v147, v126
	v_fmac_f32_e32 v63, v149, v127
	v_lshlrev_b32_e32 v151, 16, v187
	v_and_b32_e32 v153, 0xffff0000, v187
	v_fmac_f32_e32 v64, v151, v128
	v_fmac_f32_e32 v65, v153, v129
	s_add_u32 s13, s13, 1
	s_cmp_lt_u32 s13, 8
	s_cbranch_scc1 .Lmg_seg
; DI u16 f2bf(float x) { return (u16)(pack2(x, 0.f) & 0xffffu); }
; DI int crow(int i, int h) { return (i & 3) + 8 * (i >> 2) + 4 * h; }
; DI void phase_merge(const Params& p, int l, char* smem, int tid) {
;     ...
; #pragma unroll
;     for (int nb = 0; nb < 2; nb++) {
;       const int rowb = m0 + wm * 32, col = n0 + wn * 64 + nb * 32 + r;
; #pragma unroll
;       for (int i = 0; i < 16; i++) ACC[(size_t)(rowb + crow(i, h)) * 1024 + col] = f2bf(accT[0][nb][i]);
;     }
	s_sub_u32 s6, s2, s96
	s_subb_u32 s7, s3, s97
	s_add_u32 s6, s6, s90
	s_addc_u32 s7, s7, s91
	s_lshr_b32 s8, s19, 10
	s_add_u32 s6, s6, s8
	s_addc_u32 s7, s7, 0
	v_cvt_pk_bf16_f32 v66, v2, v3
	v_cvt_pk_bf16_f32 v67, v4, v5
	ds_write_b64 v134, v[66:67] offset:0
	v_cvt_pk_bf16_f32 v68, v6, v7
	v_cvt_pk_bf16_f32 v69, v8, v9
	ds_write_b64 v134, v[68:69] offset:16
	v_cvt_pk_bf16_f32 v70, v10, v11
	v_cvt_pk_bf16_f32 v71, v12, v13
	ds_write_b64 v134, v[70:71] offset:32
	v_cvt_pk_bf16_f32 v72, v14, v15
	v_cvt_pk_bf16_f32 v73, v16, v17
	ds_write_b64 v134, v[72:73] offset:48
	v_cvt_pk_bf16_f32 v66, v18, v19
	v_cvt_pk_bf16_f32 v67, v20, v21
	ds_write_b64 v134, v[66:67] offset:64
	v_cvt_pk_bf16_f32 v68, v22, v23
	v_cvt_pk_bf16_f32 v69, v24, v25
	ds_write_b64 v134, v[68:69] offset:80
	v_cvt_pk_bf16_f32 v70, v26, v27
	v_cvt_pk_bf16_f32 v71, v28, v29
	ds_write_b64 v134, v[70:71] offset:96
	v_cvt_pk_bf16_f32 v72, v30, v31
	v_cvt_pk_bf16_f32 v73, v32, v33
	ds_write_b64 v134, v[72:73] offset:112
	v_cvt_pk_bf16_f32 v66, v34, v35
	v_cvt_pk_bf16_f32 v67, v36, v37
	ds_write_b64 v134, v[66:67] offset:4608
	v_cvt_pk_bf16_f32 v68, v38, v39
	v_cvt_pk_bf16_f32 v69, v40, v41
	ds_write_b64 v134, v[68:69] offset:4624
	v_cvt_pk_bf16_f32 v70, v42, v43
	v_cvt_pk_bf16_f32 v71, v44, v45
	ds_write_b64 v134, v[70:71] offset:4640
	v_cvt_pk_bf16_f32 v72, v46, v47
	v_cvt_pk_bf16_f32 v73, v48, v49
	ds_write_b64 v134, v[72:73] offset:4656
	v_cvt_pk_bf16_f32 v66, v50, v51
	v_cvt_pk_bf16_f32 v67, v52, v53
	ds_write_b64 v134, v[66:67] offset:4672
	v_cvt_pk_bf16_f32 v68, v54, v55
	v_cvt_pk_bf16_f32 v69, v56, v57
	ds_write_b64 v134, v[68:69] offset:4688
	v_cvt_pk_bf16_f32 v70, v58, v59
	v_cvt_pk_bf16_f32 v71, v60, v61
	ds_write_b64 v134, v[70:71] offset:4704
	v_cvt_pk_bf16_f32 v72, v62, v63
	v_cvt_pk_bf16_f32 v73, v64, v65
	ds_write_b64 v134, v[72:73] offset:4720
	ds_read_b128 v[74:77], v135 offset:0
	ds_read_b128 v[78:81], v135 offset:1152
	ds_read_b128 v[82:85], v135 offset:2304
	ds_read_b128 v[86:89], v135 offset:3456
	ds_read_b128 v[90:93], v135 offset:4608
	ds_read_b128 v[94:97], v135 offset:5760
	ds_read_b128 v[98:101], v135 offset:6912
	ds_read_b128 v[102:105], v135 offset:8064
	s_waitcnt lgkmcnt(7)
	global_store_dwordx4 v136, v[74:77], s[6:7] nt
	s_add_u32 s6, s6, 0x4000
	s_addc_u32 s7, s7, 0
	s_waitcnt lgkmcnt(6)
	global_store_dwordx4 v136, v[78:81], s[6:7] nt
	s_add_u32 s6, s6, 0x4000
	s_addc_u32 s7, s7, 0
	s_waitcnt lgkmcnt(5)
	global_store_dwordx4 v136, v[82:85], s[6:7] nt
	s_add_u32 s6, s6, 0x4000
	s_addc_u32 s7, s7, 0
	s_waitcnt lgkmcnt(4)
	global_store_dwordx4 v136, v[86:89], s[6:7] nt
	s_add_u32 s6, s6, 0x4000
	s_addc_u32 s7, s7, 0
	s_waitcnt lgkmcnt(3)
	global_store_dwordx4 v136, v[90:93], s[6:7] nt
	s_add_u32 s6, s6, 0x4000
	s_addc_u32 s7, s7, 0
	s_waitcnt lgkmcnt(2)
	global_store_dwordx4 v136, v[94:97], s[6:7] nt
	s_add_u32 s6, s6, 0x4000
	s_addc_u32 s7, s7, 0
	s_waitcnt lgkmcnt(1)
	global_store_dwordx4 v136, v[98:101], s[6:7] nt
	s_add_u32 s6, s6, 0x4000
	s_addc_u32 s7, s7, 0
	s_waitcnt lgkmcnt(0)
	global_store_dwordx4 v136, v[102:105], s[6:7] nt
	s_cmp_eq_u32 s18, 0
	s_cbranch_scc1 .Lmg_item
	s_add_u32 s12, s12, s49
	s_branch .Lmg_item

; DI u16 f2bf(float x) { return (u16)(pack2(x, 0.f) & 0xffffu); }
; DI int crow(int i, int h) { return (i & 3) + 8 * (i >> 2) + 4 * h; }
; DI void phase_outproj(const Params& p, int l, char* smem, int tid) {
;     ...
;     gemm_main<2>(ACC + (size_t)m0 * 1024, 1024, p.WtOut + (size_t)l * 1024 * 1024 + (size_t)n0 * 1024, 1024, 1024, acc, s, tid);
;     u16* O = p.G;
; #pragma unroll
;     for (int mb = 0; mb < 2; mb++)
; #pragma unroll
;       for (int nb = 0; nb < 2; nb++) {
;         const int rowb = m0 + wm * 64 + mb * 32, col = n0 + wn * 64 + nb * 32 + r;
;         const int b = rowb / SEQA, pos0 = rowb % SEQA;
;         const float gate = p.mod[((size_t)l * 9 + ((pos0 < CTXL) ? 8 : b)) * 3072 + 2048 + col];
; #pragma unroll
;         for (int i = 0; i < 16; i++) O[(size_t)(rowb + crow(i, h)) * 1024 + col] = f2bf(gate * acc[mb][nb][i]);
;       }
.Lop_last:
	ds_read_b128 v[82:85], v103 offset:32768
	ds_read_b128 v[90:93], v107 offset:32768
	ds_read_b128 v[86:89], v103 offset:36864
	ds_read_b128 v[94:97], v107 offset:36864
	s_waitcnt lgkmcnt(4)
	v_mfma_f32_32x32x16_bf16 v[2:17], v[74:77], v[66:69], v[2:17]
	v_mfma_f32_32x32x16_bf16 v[18:33], v[78:81], v[66:69], v[18:33]
	v_mfma_f32_32x32x16_bf16 v[34:49], v[74:77], v[70:73], v[34:49]
	v_mfma_f32_32x32x16_bf16 v[50:65], v[78:81], v[70:73], v[50:65]
	ds_read_b128 v[66:69], v104 offset:32768
	ds_read_b128 v[74:77], v108 offset:32768
	ds_read_b128 v[70:73], v104 offset:36864
	ds_read_b128 v[78:81], v108 offset:36864
	s_waitcnt lgkmcnt(4)
	v_mfma_f32_32x32x16_bf16 v[2:17], v[90:93], v[82:85], v[2:17]
	v_mfma_f32_32x32x16_bf16 v[18:33], v[94:97], v[82:85], v[18:33]
	v_mfma_f32_32x32x16_bf16 v[34:49], v[90:93], v[86:89], v[34:49]
	v_mfma_f32_32x32x16_bf16 v[50:65], v[94:97], v[86:89], v[50:65]
	ds_read_b128 v[82:85], v105 offset:32768
	ds_read_b128 v[90:93], v109 offset:32768
	ds_read_b128 v[86:89], v105 offset:36864
	ds_read_b128 v[94:97], v109 offset:36864
	s_waitcnt lgkmcnt(4)
	v_mfma_f32_32x32x16_bf16 v[2:17], v[74:77], v[66:69], v[2:17]
	v_mfma_f32_32x32x16_bf16 v[18:33], v[78:81], v[66:69], v[18:33]
	v_mfma_f32_32x32x16_bf16 v[34:49], v[74:77], v[70:73], v[34:49]
	v_mfma_f32_32x32x16_bf16 v[50:65], v[78:81], v[70:73], v[50:65]
	s_waitcnt vmcnt(0) lgkmcnt(0)
	s_barrier
	v_mfma_f32_32x32x16_bf16 v[2:17], v[90:93], v[82:85], v[2:17]
	v_mfma_f32_32x32x16_bf16 v[18:33], v[94:97], v[82:85], v[18:33]
	v_mfma_f32_32x32x16_bf16 v[34:49], v[90:93], v[86:89], v[34:49]
	v_mfma_f32_32x32x16_bf16 v[50:65], v[94:97], v[86:89], v[50:65]
	s_nop 7
	s_nop 7
	v_mul_f32_e32 v2, v116, v2
	v_mul_f32_e32 v3, v117, v3
	v_mul_f32_e32 v4, v118, v4
	v_mul_f32_e32 v5, v119, v5
	v_mul_f32_e32 v6, v120, v6
	v_mul_f32_e32 v7, v121, v7
	v_mul_f32_e32 v8, v122, v8
	v_mul_f32_e32 v9, v123, v9
	v_mul_f32_e32 v10, v124, v10
	v_mul_f32_e32 v11, v125, v11
	v_mul_f32_e32 v12, v126, v12
	v_mul_f32_e32 v13, v127, v13
	v_mul_f32_e32 v14, v128, v14
	v_mul_f32_e32 v15, v129, v15
	v_mul_f32_e32 v16, v130, v16
	v_mul_f32_e32 v17, v131, v17
	v_mul_f32_e32 v18, v132, v18
	v_mul_f32_e32 v19, v133, v19
	v_mul_f32_e32 v20, v134, v20
	v_mul_f32_e32 v21, v135, v21
	v_mul_f32_e32 v22, v136, v22
	v_mul_f32_e32 v23, v137, v23
	v_mul_f32_e32 v24, v138, v24
	v_mul_f32_e32 v25, v139, v25
	v_mul_f32_e32 v26, v140, v26
	v_mul_f32_e32 v27, v141, v27
	v_mul_f32_e32 v28, v142, v28
	v_mul_f32_e32 v29, v143, v29
	v_mul_f32_e32 v30, v144, v30
	v_mul_f32_e32 v31, v145, v31
	v_mul_f32_e32 v32, v146, v32
	v_mul_f32_e32 v33, v147, v33
	v_mul_f32_e32 v34, v116, v34
	v_mul_f32_e32 v35, v117, v35
	v_mul_f32_e32 v36, v118, v36
	v_mul_f32_e32 v37, v119, v37
	v_mul_f32_e32 v38, v120, v38
	v_mul_f32_e32 v39, v121, v39
	v_mul_f32_e32 v40, v122, v40
	v_mul_f32_e32 v41, v123, v41
	v_mul_f32_e32 v42, v124, v42
	v_mul_f32_e32 v43, v125, v43
	v_mul_f32_e32 v44, v126, v44
	v_mul_f32_e32 v45, v127, v45
	v_mul_f32_e32 v46, v128, v46
	v_mul_f32_e32 v47, v129, v47
	v_mul_f32_e32 v48, v130, v48
	v_mul_f32_e32 v49, v131, v49
	v_mul_f32_e32 v50, v132, v50
	v_mul_f32_e32 v51, v133, v51
	v_mul_f32_e32 v52, v134, v52
	v_mul_f32_e32 v53, v135, v53
	v_mul_f32_e32 v54, v136, v54
	v_mul_f32_e32 v55, v137, v55
	v_mul_f32_e32 v56, v138, v56
	v_mul_f32_e32 v57, v139, v57
	v_mul_f32_e32 v58, v140, v58
	v_mul_f32_e32 v59, v141, v59
	v_mul_f32_e32 v60, v142, v60
	v_mul_f32_e32 v61, v143, v61
	v_mul_f32_e32 v62, v144, v62
	v_mul_f32_e32 v63, v145, v63
	v_mul_f32_e32 v64, v146, v64
	v_mul_f32_e32 v65, v147, v65
	v_cvt_pk_bf16_f32 v156, v2, v3
	v_cvt_pk_bf16_f32 v157, v4, v5
	ds_write_b64 v164, v[156:157] offset:0
	v_cvt_pk_bf16_f32 v158, v6, v7
	v_cvt_pk_bf16_f32 v159, v8, v9
	ds_write_b64 v164, v[158:159] offset:16
	v_cvt_pk_bf16_f32 v160, v10, v11
	v_cvt_pk_bf16_f32 v161, v12, v13
	ds_write_b64 v164, v[160:161] offset:32
	v_cvt_pk_bf16_f32 v162, v14, v15
	v_cvt_pk_bf16_f32 v163, v16, v17
	ds_write_b64 v164, v[162:163] offset:48
	v_cvt_pk_bf16_f32 v156, v18, v19
	v_cvt_pk_bf16_f32 v157, v20, v21
	ds_write_b64 v164, v[156:157] offset:64
	v_cvt_pk_bf16_f32 v158, v22, v23
	v_cvt_pk_bf16_f32 v159, v24, v25
	ds_write_b64 v164, v[158:159] offset:80
	v_cvt_pk_bf16_f32 v160, v26, v27
	v_cvt_pk_bf16_f32 v161, v28, v29
	ds_write_b64 v164, v[160:161] offset:96
	v_cvt_pk_bf16_f32 v162, v30, v31
	v_cvt_pk_bf16_f32 v163, v32, v33
	ds_write_b64 v164, v[162:163] offset:112
	v_cvt_pk_bf16_f32 v156, v34, v35
	v_cvt_pk_bf16_f32 v157, v36, v37
	ds_write_b64 v164, v[156:157] offset:4608
	v_cvt_pk_bf16_f32 v158, v38, v39
	v_cvt_pk_bf16_f32 v159, v40, v41
	ds_write_b64 v164, v[158:159] offset:4624
	v_cvt_pk_bf16_f32 v160, v42, v43
	v_cvt_pk_bf16_f32 v161, v44, v45
	ds_write_b64 v164, v[160:161] offset:4640
	v_cvt_pk_bf16_f32 v162, v46, v47
	v_cvt_pk_bf16_f32 v163, v48, v49
	ds_write_b64 v164, v[162:163] offset:4656
	v_cvt_pk_bf16_f32 v156, v50, v51
	v_cvt_pk_bf16_f32 v157, v52, v53
	ds_write_b64 v164, v[156:157] offset:4672
	v_cvt_pk_bf16_f32 v158, v54, v55
	v_cvt_pk_bf16_f32 v159, v56, v57
	ds_write_b64 v164, v[158:159] offset:4688
	v_cvt_pk_bf16_f32 v160, v58, v59
	v_cvt_pk_bf16_f32 v161, v60, v61
	ds_write_b64 v164, v[160:161] offset:4704
	v_cvt_pk_bf16_f32 v162, v62, v63
	v_cvt_pk_bf16_f32 v163, v64, v65
	ds_write_b64 v164, v[162:163] offset:4720
	ds_read_b128 v[66:69], v165 offset:0
	ds_read_b128 v[70:73], v165 offset:1152
	ds_read_b128 v[74:77], v165 offset:2304
	ds_read_b128 v[78:81], v165 offset:3456
	ds_read_b128 v[82:85], v165 offset:4608
	ds_read_b128 v[86:89], v165 offset:5760
	ds_read_b128 v[90:93], v165 offset:6912
	ds_read_b128 v[94:97], v165 offset:8064
	s_waitcnt lgkmcnt(7)
	global_store_dwordx4 v166, v[66:69], s[16:17] nt
	s_add_u32 s16, s16, 0x4000
	s_addc_u32 s17, s17, 0
	s_waitcnt lgkmcnt(6)
	global_store_dwordx4 v166, v[70:73], s[16:17] nt
	s_add_u32 s16, s16, 0x4000
	s_addc_u32 s17, s17, 0
	s_waitcnt lgkmcnt(5)
	global_store_dwordx4 v166, v[74:77], s[16:17] nt
	s_add_u32 s16, s16, 0x4000
	s_addc_u32 s17, s17, 0
	s_waitcnt lgkmcnt(4)
	global_store_dwordx4 v166, v[78:81], s[16:17] nt
	s_add_u32 s16, s16, 0x4000
	s_addc_u32 s17, s17, 0
	s_waitcnt lgkmcnt(3)
	global_store_dwordx4 v166, v[82:85], s[16:17] nt
	s_add_u32 s16, s16, 0x4000
	s_addc_u32 s17, s17, 0
	s_waitcnt lgkmcnt(2)
	global_store_dwordx4 v166, v[86:89], s[16:17] nt
	s_add_u32 s16, s16, 0x4000
	s_addc_u32 s17, s17, 0
	s_waitcnt lgkmcnt(1)
	global_store_dwordx4 v166, v[90:93], s[16:17] nt
	s_add_u32 s16, s16, 0x4000
	s_addc_u32 s17, s17, 0
	s_waitcnt lgkmcnt(0)
	global_store_dwordx4 v166, v[94:97], s[16:17] nt
	s_cmp_eq_u32 s18, 0
	s_cbranch_scc1 .Lop_item
	s_add_u32 s12, s12, s49
	s_branch .Lop_item
